# plus: GEMM unit-start accumulator clear with 64 v_mov_b64 instead of 128 v_mov_b32
# speedup vs baseline: 1.0026x; 1.0026x over previous
.LBB0_71:
	s_add_u32 s0, s0, 0x40080
	s_addc_u32 s1, s1, 0
	s_add_u32 s25, s4, 0x100
	v_mov_b64_e32 v[2:3], 0
	v_mov_b64_e32 v[4:5], 0
	v_mov_b64_e32 v[6:7], 0
	v_mov_b64_e32 v[8:9], 0
	v_mov_b64_e32 v[10:11], 0
	v_mov_b64_e32 v[12:13], 0
	v_mov_b64_e32 v[14:15], 0
	v_mov_b64_e32 v[16:17], 0
	v_mov_b64_e32 v[18:19], 0
	v_mov_b64_e32 v[20:21], 0
	v_mov_b64_e32 v[22:23], 0
	v_mov_b64_e32 v[24:25], 0
	v_mov_b64_e32 v[26:27], 0
	v_mov_b64_e32 v[28:29], 0
	v_mov_b64_e32 v[30:31], 0
	v_mov_b64_e32 v[32:33], 0
	v_mov_b64_e32 v[50:51], 0
	v_mov_b64_e32 v[52:53], 0
	v_mov_b64_e32 v[54:55], 0
	v_mov_b64_e32 v[56:57], 0
	v_mov_b64_e32 v[58:59], 0
	v_mov_b64_e32 v[60:61], 0
	v_mov_b64_e32 v[62:63], 0
	v_mov_b64_e32 v[64:65], 0
	v_mov_b64_e32 v[66:67], 0
	v_mov_b64_e32 v[68:69], 0
	v_mov_b64_e32 v[70:71], 0
	v_mov_b64_e32 v[72:73], 0
	v_mov_b64_e32 v[74:75], 0
	v_mov_b64_e32 v[76:77], 0
	v_mov_b64_e32 v[78:79], 0
	v_mov_b64_e32 v[80:81], 0
	v_mov_b64_e32 v[82:83], 0
	v_mov_b64_e32 v[84:85], 0
	v_mov_b64_e32 v[86:87], 0
	v_mov_b64_e32 v[88:89], 0
	v_mov_b64_e32 v[90:91], 0
	v_mov_b64_e32 v[92:93], 0
	v_mov_b64_e32 v[94:95], 0
	v_mov_b64_e32 v[96:97], 0
	v_mov_b64_e32 v[98:99], 0
	v_mov_b64_e32 v[100:101], 0
	v_mov_b64_e32 v[102:103], 0
	v_mov_b64_e32 v[104:105], 0
	v_mov_b64_e32 v[106:107], 0
	v_mov_b64_e32 v[108:109], 0
	v_mov_b64_e32 v[110:111], 0
	v_mov_b64_e32 v[112:113], 0
	v_mov_b64_e32 v[114:115], 0
	v_mov_b64_e32 v[116:117], 0
	v_mov_b64_e32 v[118:119], 0
	v_mov_b64_e32 v[120:121], 0
	v_mov_b64_e32 v[122:123], 0
	v_mov_b64_e32 v[124:125], 0
	v_mov_b64_e32 v[126:127], 0
	v_mov_b64_e32 v[128:129], 0
	v_mov_b64_e32 v[130:131], 0
	v_mov_b64_e32 v[132:133], 0
	v_mov_b64_e32 v[134:135], 0
	v_mov_b64_e32 v[136:137], 0
	v_mov_b64_e32 v[138:139], 0
	v_mov_b64_e32 v[140:141], 0
	v_mov_b64_e32 v[142:143], 0
	v_mov_b64_e32 v[144:145], 0
	s_addc_u32 s26, s5, 0
	s_mov_b32 s27, -2

.LBB0_146:
	s_add_u32 s0, s0, 0x40080
	s_addc_u32 s1, s1, 0
	s_add_u32 s2, s4, 0x100
	v_mov_b64_e32 v[2:3], 0
	v_mov_b64_e32 v[4:5], 0
	v_mov_b64_e32 v[6:7], 0
	v_mov_b64_e32 v[8:9], 0
	v_mov_b64_e32 v[10:11], 0
	v_mov_b64_e32 v[12:13], 0
	v_mov_b64_e32 v[14:15], 0
	v_mov_b64_e32 v[16:17], 0
	v_mov_b64_e32 v[18:19], 0
	v_mov_b64_e32 v[20:21], 0
	v_mov_b64_e32 v[22:23], 0
	v_mov_b64_e32 v[24:25], 0
	v_mov_b64_e32 v[26:27], 0
	v_mov_b64_e32 v[28:29], 0
	v_mov_b64_e32 v[30:31], 0
	v_mov_b64_e32 v[32:33], 0
	v_mov_b64_e32 v[34:35], 0
	v_mov_b64_e32 v[36:37], 0
	v_mov_b64_e32 v[38:39], 0
	v_mov_b64_e32 v[40:41], 0
	v_mov_b64_e32 v[42:43], 0
	v_mov_b64_e32 v[44:45], 0
	v_mov_b64_e32 v[46:47], 0
	v_mov_b64_e32 v[48:49], 0
	v_mov_b64_e32 v[50:51], 0
	v_mov_b64_e32 v[52:53], 0
	v_mov_b64_e32 v[54:55], 0
	v_mov_b64_e32 v[56:57], 0
	v_mov_b64_e32 v[58:59], 0
	v_mov_b64_e32 v[60:61], 0
	v_mov_b64_e32 v[62:63], 0
	v_mov_b64_e32 v[64:65], 0
	v_mov_b64_e32 v[66:67], 0
	v_mov_b64_e32 v[68:69], 0
	v_mov_b64_e32 v[70:71], 0
	v_mov_b64_e32 v[72:73], 0
	v_mov_b64_e32 v[74:75], 0
	v_mov_b64_e32 v[76:77], 0
	v_mov_b64_e32 v[78:79], 0
	v_mov_b64_e32 v[80:81], 0
	v_mov_b64_e32 v[82:83], 0
	v_mov_b64_e32 v[84:85], 0
	v_mov_b64_e32 v[86:87], 0
	v_mov_b64_e32 v[88:89], 0
	v_mov_b64_e32 v[90:91], 0
	v_mov_b64_e32 v[92:93], 0
	v_mov_b64_e32 v[94:95], 0
	v_mov_b64_e32 v[96:97], 0
	v_mov_b64_e32 v[98:99], 0
	v_mov_b64_e32 v[100:101], 0
	v_mov_b64_e32 v[102:103], 0
	v_mov_b64_e32 v[104:105], 0
	v_mov_b64_e32 v[106:107], 0
	v_mov_b64_e32 v[108:109], 0
	v_mov_b64_e32 v[110:111], 0
	v_mov_b64_e32 v[112:113], 0
	v_mov_b64_e32 v[114:115], 0
	v_mov_b64_e32 v[116:117], 0
	v_mov_b64_e32 v[118:119], 0
	v_mov_b64_e32 v[120:121], 0
	v_mov_b64_e32 v[122:123], 0
	v_mov_b64_e32 v[124:125], 0
	v_mov_b64_e32 v[126:127], 0
	v_mov_b64_e32 v[128:129], 0
	s_addc_u32 s3, s5, 0
	s_mov_b32 s8, -2

.LBB0_459:
	s_add_u32 s33, s4, s18
	s_addc_u32 s36, s5, 0
	s_cmp_gt_i32 s3, 31
	s_cselect_b64 s[8:9], -1, 0
	s_lshl_b32 s10, s3, 4
	s_addk_i32 s10, 0xfe00
	s_ashr_i32 s11, s10, 31
	s_lshl_b64 s[10:11], s[10:11], 2
	s_add_u32 s10, s26, s10
	v_mov_b64_e32 v[2:3], 0
	v_mov_b64_e32 v[4:5], 0
	v_mov_b64_e32 v[6:7], 0
	v_mov_b64_e32 v[8:9], 0
	v_mov_b64_e32 v[10:11], 0
	v_mov_b64_e32 v[12:13], 0
	v_mov_b64_e32 v[14:15], 0
	v_mov_b64_e32 v[16:17], 0
	v_mov_b64_e32 v[18:19], 0
	v_mov_b64_e32 v[20:21], 0
	v_mov_b64_e32 v[22:23], 0
	v_mov_b64_e32 v[24:25], 0
	v_mov_b64_e32 v[26:27], 0
	v_mov_b64_e32 v[28:29], 0
	v_mov_b64_e32 v[30:31], 0
	v_mov_b64_e32 v[32:33], 0
	v_mov_b64_e32 v[34:35], 0
	v_mov_b64_e32 v[36:37], 0
	v_mov_b64_e32 v[38:39], 0
	v_mov_b64_e32 v[40:41], 0
	v_mov_b64_e32 v[42:43], 0
	v_mov_b64_e32 v[44:45], 0
	v_mov_b64_e32 v[46:47], 0
	v_mov_b64_e32 v[48:49], 0
	v_mov_b64_e32 v[50:51], 0
	v_mov_b64_e32 v[52:53], 0
	v_mov_b64_e32 v[54:55], 0
	v_mov_b64_e32 v[56:57], 0
	v_mov_b64_e32 v[58:59], 0
	v_mov_b64_e32 v[60:61], 0
	v_mov_b64_e32 v[62:63], 0
	v_mov_b64_e32 v[64:65], 0
	v_mov_b64_e32 v[66:67], 0
	v_mov_b64_e32 v[68:69], 0
	v_mov_b64_e32 v[70:71], 0
	v_mov_b64_e32 v[72:73], 0
	v_mov_b64_e32 v[74:75], 0
	v_mov_b64_e32 v[76:77], 0
	v_mov_b64_e32 v[78:79], 0
	v_mov_b64_e32 v[80:81], 0
	v_mov_b64_e32 v[82:83], 0
	v_mov_b64_e32 v[84:85], 0
	v_mov_b64_e32 v[86:87], 0
	v_mov_b64_e32 v[88:89], 0
	v_mov_b64_e32 v[90:91], 0
	v_mov_b64_e32 v[92:93], 0
	v_mov_b64_e32 v[94:95], 0
	v_mov_b64_e32 v[96:97], 0
	v_mov_b64_e32 v[98:99], 0
	v_mov_b64_e32 v[100:101], 0
	v_mov_b64_e32 v[102:103], 0
	v_mov_b64_e32 v[104:105], 0
	v_mov_b64_e32 v[106:107], 0
	v_mov_b64_e32 v[108:109], 0
	v_mov_b64_e32 v[110:111], 0
	v_mov_b64_e32 v[112:113], 0
	v_mov_b64_e32 v[114:115], 0
	v_mov_b64_e32 v[116:117], 0
	v_mov_b64_e32 v[118:119], 0
	v_mov_b64_e32 v[120:121], 0
	v_mov_b64_e32 v[122:123], 0
	v_mov_b64_e32 v[124:125], 0
	v_mov_b64_e32 v[126:127], 0
	v_mov_b64_e32 v[128:129], 0
	s_addc_u32 s11, s25, s11
	s_mov_b32 s37, 0
	s_branch .LBB0_463

.LBB0_826:
	s_add_u32 s4, s4, 0x40080
	s_addc_u32 s5, s5, 0
	s_add_u32 s33, s6, 0x100
	v_mov_b64_e32 v[2:3], 0
	v_mov_b64_e32 v[4:5], 0
	v_mov_b64_e32 v[6:7], 0
	v_mov_b64_e32 v[8:9], 0
	v_mov_b64_e32 v[10:11], 0
	v_mov_b64_e32 v[12:13], 0
	v_mov_b64_e32 v[14:15], 0
	v_mov_b64_e32 v[16:17], 0
	v_mov_b64_e32 v[18:19], 0
	v_mov_b64_e32 v[20:21], 0
	v_mov_b64_e32 v[22:23], 0
	v_mov_b64_e32 v[24:25], 0
	v_mov_b64_e32 v[26:27], 0
	v_mov_b64_e32 v[28:29], 0
	v_mov_b64_e32 v[30:31], 0
	v_mov_b64_e32 v[32:33], 0
	v_mov_b64_e32 v[34:35], 0
	v_mov_b64_e32 v[36:37], 0
	v_mov_b64_e32 v[38:39], 0
	v_mov_b64_e32 v[40:41], 0
	v_mov_b64_e32 v[42:43], 0
	v_mov_b64_e32 v[44:45], 0
	v_mov_b64_e32 v[46:47], 0
	v_mov_b64_e32 v[48:49], 0
	v_mov_b64_e32 v[50:51], 0
	v_mov_b64_e32 v[52:53], 0
	v_mov_b64_e32 v[54:55], 0
	v_mov_b64_e32 v[56:57], 0
	v_mov_b64_e32 v[58:59], 0
	v_mov_b64_e32 v[60:61], 0
	v_mov_b64_e32 v[62:63], 0
	v_mov_b64_e32 v[64:65], 0
	v_mov_b64_e32 v[82:83], 0
	v_mov_b64_e32 v[84:85], 0
	v_mov_b64_e32 v[86:87], 0
	v_mov_b64_e32 v[88:89], 0
	v_mov_b64_e32 v[90:91], 0
	v_mov_b64_e32 v[92:93], 0
	v_mov_b64_e32 v[94:95], 0
	v_mov_b64_e32 v[96:97], 0
	v_mov_b64_e32 v[98:99], 0
	v_mov_b64_e32 v[100:101], 0
	v_mov_b64_e32 v[102:103], 0
	v_mov_b64_e32 v[104:105], 0
	v_mov_b64_e32 v[106:107], 0
	v_mov_b64_e32 v[108:109], 0
	v_mov_b64_e32 v[110:111], 0
	v_mov_b64_e32 v[112:113], 0
	v_mov_b64_e32 v[114:115], 0
	v_mov_b64_e32 v[116:117], 0
	v_mov_b64_e32 v[118:119], 0
	v_mov_b64_e32 v[120:121], 0
	v_mov_b64_e32 v[122:123], 0
	v_mov_b64_e32 v[124:125], 0
	v_mov_b64_e32 v[126:127], 0
	v_mov_b64_e32 v[128:129], 0
	v_mov_b64_e32 v[130:131], 0
	v_mov_b64_e32 v[132:133], 0
	v_mov_b64_e32 v[134:135], 0
	v_mov_b64_e32 v[136:137], 0
	v_mov_b64_e32 v[138:139], 0
	v_mov_b64_e32 v[140:141], 0
	v_mov_b64_e32 v[142:143], 0
	v_mov_b64_e32 v[144:145], 0
	s_addc_u32 s55, s7, 0
	s_mov_b32 s56, -2
